# attention unit epilogues: output-gain loads issued together and waited once (DA 16 loads, MLA and SB 8 loads each) instead of one drain per chunk
# speedup vs baseline: 1.0269x; 1.0007x over previous
; DI unsigned cvtpk(float lo, float hi) { f32x2_t v = {lo, hi}; bf16x2_t b = __builtin_convertvector(v, bf16x2_t); return __builtin_bit_cast(unsigned, b); }
; DI float shx(float v, int mask, int lane) { return __builtin_bit_cast(float, __builtin_amdgcn_ds_bpermute((lane ^ mask) << 2, __builtin_bit_cast(int, v))); }
; template <int MODE>
; DI void attn_unit(LAS unsigned char* lds, const bf16_t* Qg, int ldq, const bf16_t* Kg, int ldk, const bf16_t* VTg, int ldvt, bf16_t* Og, int ldo,
;                   int q0, int NT, const float* gout, const float* relb, float lam, float osc, const float* qgain) {
;     ...
;     if (MODE != 2) { const float lt = lrun + shx(lrun, 32, lane); inv = 1.f / lt; }
;     ...
;         float rs = inv;
;         if (MODE == 1 || MODE == 2) {
;             float ss = 0.f;
; #pragma unroll
;             for (int d = 0; d < NDB; ++d)
; #pragma unroll
;                 for (int i = 0; i < 16; ++i) { const float v = o[d][i] * inv; ss += v * v; }
;             ss += shx(ss, 32, lane);
;             rs = inv * rsqrtf(ss * (1.f / 64.f) + EPS);
;         }
;         bf16_t* opb = Og + (size_t)qrow * ldo + (MODE == 2 ? mm * 64 : 0);
; #pragma unroll
;         for (int d = 0; d < NDB; ++d) { u32x2 wq[4];
; #pragma unroll
;             for (int g = 0; g < 4; ++g) { f32x4 gv = (f32x4){1.f, 1.f, 1.f, 1.f}; if (MODE != 3) gv = *(const f32x4*)(gout + 32 * d + 8 * g + 4 * hi);
;                 u32x2 w; w.x = cvtpk(o[d][4 * g] * rs * gv[0], o[d][4 * g + 1] * rs * gv[1]); w.y = cvtpk(o[d][4 * g + 2] * rs * gv[2], o[d][4 * g + 3] * rs * gv[3]);
;                 wq[g] = w; }
;             AT_STORE16(opb, d); }
.LBB0_95:
	ds_bpermute_b32 v0, v129, v133
	s_lshl_b64 s[0:1], s[16:17], 22
	v_readlane_b32 s2, v254, 12
	v_readlane_b32 s3, v254, 13
	s_add_u32 s0, s2, s0
	s_addc_u32 s1, s3, s1
	s_lshl_b32 s2, s8, 1
	s_waitcnt lgkmcnt(0)
	v_add_f32_e32 v0, v133, v0
	s_add_u32 s0, s0, s2
	s_waitcnt vmcnt(0)
	v_div_scale_f32 v2, s[2:3], v0, v0, 1.0
	v_rcp_f32_e32 v3, v2
	s_addc_u32 s1, s1, 0
	s_barrier
	v_fma_f32 v4, -v2, v3, 1.0
	v_fmac_f32_e32 v3, v4, v3
	v_div_scale_f32 v4, vcc, 1.0, v0, 1.0
	v_mul_f32_e32 v5, v4, v3
	v_fma_f32 v6, -v2, v5, v4
	v_fmac_f32_e32 v5, v6, v3
	v_fma_f32 v2, -v2, v5, v4
	v_div_fmas_f32 v2, v2, v3, v5
	v_div_fixup_f32 v0, v2, v0, 1.0
	v_mul_f32_e32 v3, v33, v0
	v_mul_f32_e32 v2, v32, v0
	v_mul_f32_e32 v4, v3, v3
	v_fmac_f32_e32 v4, v2, v2
	v_mul_f32_e32 v2, v34, v0
	v_fmac_f32_e32 v4, v2, v2
	v_mul_f32_e32 v2, v35, v0
	v_fmac_f32_e32 v4, v2, v2
	v_mul_f32_e32 v2, v36, v0
	v_fmac_f32_e32 v4, v2, v2
	v_mul_f32_e32 v2, v37, v0
	v_fmac_f32_e32 v4, v2, v2
	v_mul_f32_e32 v2, v38, v0
	v_fmac_f32_e32 v4, v2, v2
	v_mul_f32_e32 v2, v39, v0
	v_fmac_f32_e32 v4, v2, v2
	v_mul_f32_e32 v2, v40, v0
	v_fmac_f32_e32 v4, v2, v2
	v_mul_f32_e32 v2, v41, v0
	v_fmac_f32_e32 v4, v2, v2
	v_mul_f32_e32 v2, v42, v0
	v_fmac_f32_e32 v4, v2, v2
	v_mul_f32_e32 v2, v43, v0
	v_fmac_f32_e32 v4, v2, v2
	v_mul_f32_e32 v2, v44, v0
	v_fmac_f32_e32 v4, v2, v2
	v_mul_f32_e32 v2, v45, v0
	v_fmac_f32_e32 v4, v2, v2
	v_mul_f32_e32 v2, v46, v0
	v_fmac_f32_e32 v4, v2, v2
	v_mul_f32_e32 v2, v47, v0
	v_fmac_f32_e32 v4, v2, v2
	v_mul_f32_e32 v2, v16, v0
	v_fmac_f32_e32 v4, v2, v2
	v_mul_f32_e32 v2, v17, v0
	v_fmac_f32_e32 v4, v2, v2
	v_mul_f32_e32 v2, v18, v0
	v_fmac_f32_e32 v4, v2, v2
	v_mul_f32_e32 v2, v19, v0
	v_fmac_f32_e32 v4, v2, v2
	v_mul_f32_e32 v2, v20, v0
	v_fmac_f32_e32 v4, v2, v2
	v_mul_f32_e32 v2, v21, v0
	v_fmac_f32_e32 v4, v2, v2
	v_pk_mul_f32 v[2:3], v[22:23], v[0:1] op_sel_hi:[1,0]
	s_nop 0
	v_pk_mul_f32 v[2:3], v[2:3], v[2:3]
	s_nop 0
	v_add_f32_e32 v2, v2, v4
	v_add_f32_e32 v4, v3, v2
	v_pk_mul_f32 v[2:3], v[24:25], v[0:1] op_sel_hi:[1,0]
	s_nop 0
	v_pk_mul_f32 v[2:3], v[2:3], v[2:3]
	s_nop 0
	v_add_f32_e32 v2, v2, v4
	v_add_f32_e32 v4, v3, v2
	v_pk_mul_f32 v[2:3], v[26:27], v[0:1] op_sel_hi:[1,0]
	s_nop 0
	v_pk_mul_f32 v[2:3], v[2:3], v[2:3]
	s_nop 0
	v_add_f32_e32 v2, v2, v4
	v_add_f32_e32 v4, v3, v2
	v_pk_mul_f32 v[2:3], v[28:29], v[0:1] op_sel_hi:[1,0]
	s_nop 0
	v_pk_mul_f32 v[2:3], v[2:3], v[2:3]
	s_nop 0
	v_add_f32_e32 v2, v2, v4
	v_add_f32_e32 v4, v3, v2
	v_pk_mul_f32 v[2:3], v[30:31], v[0:1] op_sel_hi:[1,0]
	s_nop 0
	v_pk_mul_f32 v[2:3], v[2:3], v[2:3]
	s_nop 0
	v_add_f32_e32 v2, v2, v4
	v_add_f32_e32 v2, v3, v2
	ds_bpermute_b32 v3, v129, v2
	s_waitcnt lgkmcnt(0)
	v_add_f32_e32 v2, v2, v3
	v_fmamk_f32 v2, v2, 0x3c800000, v228
	v_cmp_gt_f32_e32 vcc, s52, v2
	v_mul_f32_e32 v3, 0x4b800000, v2
	s_nop 0
	v_cndmask_b32_e32 v2, v2, v3, vcc
	v_rsq_f32_e32 v2, v2
	s_nop 0
	v_mul_f32_e32 v3, 0x45800000, v2
	v_cndmask_b32_e32 v2, v2, v3, vcc
	v_mul_f32_e32 v8, v0, v2
	v_lshlrev_b64 v[2:3], 11, v[130:131]
	v_lshl_add_u64 v[2:3], s[0:1], 0, v[2:3]
	v_readlane_b32 s0, v254, 26
	v_lshlrev_b32_e32 v0, 1, v161
	v_readlane_b32 s1, v254, 27
	v_lshl_add_u64 v[6:7], v[2:3], 0, v[0:1]
	v_pk_mul_f32 v[10:11], v[32:33], v[8:9] op_sel_hi:[1,0]
	v_cmp_gt_u32_e32 vcc, 32, v160
	s_nop 1
	global_load_dwordx4 v[48:51], v128, s[0:1]
	global_load_dwordx4 v[52:55], v128, s[0:1] offset:32
	global_load_dwordx4 v[56:59], v128, s[0:1] offset:64
	global_load_dwordx4 v[60:63], v128, s[0:1] offset:96
	global_load_dwordx4 v[64:67], v128, s[0:1] offset:128
	global_load_dwordx4 v[68:71], v128, s[0:1] offset:160
	global_load_dwordx4 v[72:75], v128, s[0:1] offset:192
	global_load_dwordx4 v[76:79], v128, s[0:1] offset:224
	s_waitcnt vmcnt(0)
; DI unsigned cvtpk(float lo, float hi) { f32x2_t v = {lo, hi}; bf16x2_t b = __builtin_convertvector(v, bf16x2_t); return __builtin_bit_cast(unsigned, b); }
; template <int MODE>
; DI void attn_unit(LAS unsigned char* lds, const bf16_t* Qg, int ldq, const bf16_t* Kg, int ldk, const bf16_t* VTg, int ldvt, bf16_t* Og, int ldo,
;                   int q0, int NT, const float* gout, const float* relb, float lam, float osc, const float* qgain) {
;     ...
; #pragma unroll
;         for (int d = 0; d < NDB; ++d) { u32x2 wq[4];
; #pragma unroll
;             for (int g = 0; g < 4; ++g) { f32x4 gv = (f32x4){1.f, 1.f, 1.f, 1.f}; if (MODE != 3) gv = *(const f32x4*)(gout + 32 * d + 8 * g + 4 * hi);
;                 u32x2 w; w.x = cvtpk(o[d][4 * g] * rs * gv[0], o[d][4 * g + 1] * rs * gv[1]); w.y = cvtpk(o[d][4 * g + 2] * rs * gv[2], o[d][4 * g + 3] * rs * gv[3]);
;                 wq[g] = w; }
;             AT_STORE16(opb, d); }
	s_nop 1
	v_mov_b64_e32 v[2:3], v[48:49]
	v_mov_b64_e32 v[4:5], v[50:51]
	v_pk_mul_f32 v[2:3], v[2:3], v[10:11]
	s_nop 0
	v_cvt_pk_bf16_f32 v0, v2, v3
	v_pk_mul_f32 v[2:3], v[34:35], v[8:9] op_sel_hi:[1,0]
	s_nop 0
	v_pk_mul_f32 v[2:3], v[4:5], v[2:3]
	s_nop 0
	v_cvt_pk_bf16_f32 v9, v2, v3
	s_nop 1
	v_mov_b64_e32 v[2:3], v[52:53]
	v_mov_b64_e32 v[4:5], v[54:55]
	v_pk_mul_f32 v[10:11], v[36:37], v[8:9] op_sel_hi:[1,0]
	v_pk_mul_f32 v[2:3], v[2:3], v[10:11]
	s_nop 0
	v_cvt_pk_bf16_f32 v12, v2, v3
	v_pk_mul_f32 v[2:3], v[38:39], v[8:9] op_sel_hi:[1,0]
	v_pk_mul_f32 v[10:11], v[40:41], v[8:9] op_sel_hi:[1,0]
	v_pk_mul_f32 v[2:3], v[4:5], v[2:3]
	s_nop 0
	v_cvt_pk_bf16_f32 v13, v2, v3
	s_nop 1
	v_mov_b64_e32 v[2:3], v[56:57]
	v_mov_b64_e32 v[4:5], v[58:59]
	v_pk_mul_f32 v[2:3], v[2:3], v[10:11]
	s_nop 0
	v_cvt_pk_bf16_f32 v14, v2, v3
	v_pk_mul_f32 v[2:3], v[42:43], v[8:9] op_sel_hi:[1,0]
	v_pk_mul_f32 v[10:11], v[44:45], v[8:9] op_sel_hi:[1,0]
	v_pk_mul_f32 v[2:3], v[4:5], v[2:3]
	s_nop 0
	v_cvt_pk_bf16_f32 v15, v2, v3
	s_nop 1
	v_mov_b64_e32 v[2:3], v[60:61]
	v_mov_b64_e32 v[4:5], v[62:63]
	v_pk_mul_f32 v[2:3], v[2:3], v[10:11]
	s_nop 0
	v_cvt_pk_bf16_f32 v10, v2, v3
	v_pk_mul_f32 v[2:3], v[46:47], v[8:9] op_sel_hi:[1,0]
	v_cndmask_b32_e32 v34, v14, v10, vcc
	v_pk_mul_f32 v[2:3], v[4:5], v[2:3]
	s_nop 0
	v_cvt_pk_bf16_f32 v11, v2, v3
	v_cndmask_b32_e32 v2, v9, v13, vcc
	v_cndmask_b32_e32 v3, v0, v12, vcc
	ds_bpermute_b32 v32, v129, v3
	ds_bpermute_b32 v2, v129, v2
	v_cndmask_b32_e32 v33, v15, v11, vcc
	s_waitcnt lgkmcnt(1)
	v_cndmask_b32_e32 v4, v12, v32, vcc
	s_waitcnt lgkmcnt(0)
	v_cndmask_b32_e32 v5, v13, v2, vcc
	v_cndmask_b32_e32 v3, v2, v9, vcc
	v_cndmask_b32_e32 v2, v32, v0, vcc
	flat_store_dwordx4 v[6:7], v[2:5] offset:1536
	ds_bpermute_b32 v0, v129, v34
	ds_bpermute_b32 v2, v129, v33
	s_waitcnt lgkmcnt(0)
	v_cndmask_b32_e32 v4, v10, v0, vcc
	v_cndmask_b32_e32 v5, v11, v2, vcc
	v_cndmask_b32_e32 v3, v2, v15, vcc
	v_cndmask_b32_e32 v2, v0, v14, vcc
	flat_store_dwordx4 v[6:7], v[2:5] offset:1568
	s_nop 1
	v_mov_b64_e32 v[2:3], v[64:65]
	v_mov_b64_e32 v[4:5], v[66:67]
	v_pk_mul_f32 v[10:11], v[16:17], v[8:9] op_sel_hi:[1,0]
	v_pk_mul_f32 v[2:3], v[2:3], v[10:11]
	s_nop 0
	v_cvt_pk_bf16_f32 v0, v2, v3
	v_pk_mul_f32 v[2:3], v[18:19], v[8:9] op_sel_hi:[1,0]
	s_nop 0
	v_pk_mul_f32 v[2:3], v[4:5], v[2:3]
	s_nop 0
	v_cvt_pk_bf16_f32 v9, v2, v3
	s_nop 1
	v_mov_b64_e32 v[2:3], v[68:69]
	v_mov_b64_e32 v[4:5], v[70:71]
	v_pk_mul_f32 v[10:11], v[20:21], v[8:9] op_sel_hi:[1,0]
	v_pk_mul_f32 v[2:3], v[2:3], v[10:11]
	s_nop 0
	v_cvt_pk_bf16_f32 v12, v2, v3
	v_pk_mul_f32 v[2:3], v[22:23], v[8:9] op_sel_hi:[1,0]
	v_pk_mul_f32 v[10:11], v[24:25], v[8:9] op_sel_hi:[1,0]
	v_pk_mul_f32 v[2:3], v[4:5], v[2:3]
	s_nop 0
	v_cvt_pk_bf16_f32 v13, v2, v3
	s_nop 1
	v_mov_b64_e32 v[2:3], v[72:73]
	v_mov_b64_e32 v[4:5], v[74:75]
	v_pk_mul_f32 v[2:3], v[2:3], v[10:11]
	s_nop 0
	v_cvt_pk_bf16_f32 v14, v2, v3
	v_pk_mul_f32 v[2:3], v[26:27], v[8:9] op_sel_hi:[1,0]
	v_pk_mul_f32 v[10:11], v[28:29], v[8:9] op_sel_hi:[1,0]
	v_pk_mul_f32 v[2:3], v[4:5], v[2:3]
	s_nop 0
	v_cvt_pk_bf16_f32 v15, v2, v3
	s_nop 1
	v_mov_b64_e32 v[2:3], v[76:77]
	v_mov_b64_e32 v[4:5], v[78:79]
	v_pk_mul_f32 v[2:3], v[2:3], v[10:11]
	s_nop 0
	v_cvt_pk_bf16_f32 v10, v2, v3
	v_pk_mul_f32 v[2:3], v[30:31], v[8:9] op_sel_hi:[1,0]
	v_cndmask_b32_e32 v17, v14, v10, vcc
	v_pk_mul_f32 v[2:3], v[4:5], v[2:3]
	s_nop 0
	v_cvt_pk_bf16_f32 v8, v2, v3
	v_cndmask_b32_e32 v2, v9, v13, vcc
	v_cndmask_b32_e32 v3, v0, v12, vcc
	ds_bpermute_b32 v3, v129, v3
	ds_bpermute_b32 v11, v129, v2
	v_cndmask_b32_e32 v16, v15, v8, vcc
	s_waitcnt lgkmcnt(0)
	v_cndmask_b32_e32 v4, v12, v3, vcc
	v_cndmask_b32_e32 v2, v3, v0, vcc
	v_cndmask_b32_e32 v5, v13, v11, vcc
	v_cndmask_b32_e32 v3, v11, v9, vcc
	flat_store_dwordx4 v[6:7], v[2:5] offset:1600
	ds_bpermute_b32 v0, v129, v17
	ds_bpermute_b32 v3, v129, v16
	s_waitcnt lgkmcnt(0)
	v_cndmask_b32_e32 v4, v10, v0, vcc
	v_cndmask_b32_e32 v2, v0, v14, vcc
	v_cndmask_b32_e32 v5, v8, v3, vcc
	v_cndmask_b32_e32 v3, v3, v15, vcc
	flat_store_dwordx4 v[6:7], v[2:5] offset:1632

; DI unsigned cvtpk(float lo, float hi) { f32x2_t v = {lo, hi}; bf16x2_t b = __builtin_convertvector(v, bf16x2_t); return __builtin_bit_cast(unsigned, b); }
; DI float shx(float v, int mask, int lane) { return __builtin_bit_cast(float, __builtin_amdgcn_ds_bpermute((lane ^ mask) << 2, __builtin_bit_cast(int, v))); }
; template <int MODE>
; DI void attn_unit(LAS unsigned char* lds, const bf16_t* Qg, int ldq, const bf16_t* Kg, int ldk, const bf16_t* VTg, int ldvt, bf16_t* Og, int ldo,
;                   int q0, int NT, const float* gout, const float* relb, float lam, float osc, const float* qgain) {
;     ...
;         float rs = inv;
;         if (MODE == 1 || MODE == 2) {
;             float ss = 0.f;
; #pragma unroll
;             for (int d = 0; d < NDB; ++d)
; #pragma unroll
;                 for (int i = 0; i < 16; ++i) { const float v = o[d][i] * inv; ss += v * v; }
;             ss += shx(ss, 32, lane);
;             rs = inv * rsqrtf(ss * (1.f / 64.f) + EPS);
;         }
;         bf16_t* opb = Og + (size_t)qrow * ldo + (MODE == 2 ? mm * 64 : 0);
; #pragma unroll
;         for (int d = 0; d < NDB; ++d) { u32x2 wq[4];
; #pragma unroll
;             for (int g = 0; g < 4; ++g) { f32x4 gv = (f32x4){1.f, 1.f, 1.f, 1.f}; if (MODE != 3) gv = *(const f32x4*)(gout + 32 * d + 8 * g + 4 * hi);
;                 u32x2 w; w.x = cvtpk(o[d][4 * g] * rs * gv[0], o[d][4 * g + 1] * rs * gv[1]); w.y = cvtpk(o[d][4 * g + 2] * rs * gv[2], o[d][4 * g + 3] * rs * gv[3]);
;                 wq[g] = w; }
;             AT_STORE16(opb, d); }
.LBB0_141:
	v_mul_f32_e32 v44, v19, v19
	v_fmac_f32_e32 v44, v18, v18
	v_fmac_f32_e32 v44, v20, v20
	v_fmac_f32_e32 v44, v21, v21
	v_fmac_f32_e32 v44, v22, v22
	v_fmac_f32_e32 v44, v23, v23
	v_fmac_f32_e32 v44, v24, v24
	v_fmac_f32_e32 v44, v25, v25
	v_fmac_f32_e32 v44, v26, v26
	v_fmac_f32_e32 v44, v27, v27
	v_fmac_f32_e32 v44, v28, v28
	v_fmac_f32_e32 v44, v29, v29
	v_fmac_f32_e32 v44, v30, v30
	v_fmac_f32_e32 v44, v31, v31
	v_fmac_f32_e32 v44, v32, v32
	v_fmac_f32_e32 v44, v33, v33
	v_fmac_f32_e32 v44, v2, v2
	v_fmac_f32_e32 v44, v3, v3
	v_fmac_f32_e32 v44, v4, v4
	v_fmac_f32_e32 v44, v5, v5
	v_fmac_f32_e32 v44, v6, v6
	v_fmac_f32_e32 v44, v7, v7
	v_pk_mul_f32 v[42:43], v[8:9], v[8:9]
	v_pk_mul_f32 v[40:41], v[10:11], v[10:11]
	v_add_f32_e32 v42, v42, v44
	v_add_f32_e32 v42, v43, v42
	v_add_f32_e32 v40, v40, v42
	v_pk_mul_f32 v[38:39], v[12:13], v[12:13]
	v_add_f32_e32 v40, v41, v40
	v_add_f32_e32 v38, v38, v40
	v_pk_mul_f32 v[36:37], v[14:15], v[14:15]
	v_add_f32_e32 v38, v39, v38
	v_add_f32_e32 v36, v36, v38
	v_pk_mul_f32 v[34:35], v[16:17], v[16:17]
	v_add_f32_e32 v36, v37, v36
	v_add_f32_e32 v34, v34, v36
	v_add_f32_e32 v34, v35, v34
	ds_bpermute_b32 v35, v128, v34
	s_lshl_b64 s[0:1], s[16:17], 22
	v_readlane_b32 s2, v254, 12
	v_readlane_b32 s3, v254, 13
	s_add_u32 s0, s2, s0
	s_waitcnt lgkmcnt(0)
	v_add_f32_e32 v34, v34, v35
	v_fmamk_f32 v34, v34, 0x3c800000, v228
	v_cmp_gt_f32_e32 vcc, s52, v34
	v_mul_f32_e32 v35, 0x4b800000, v34
	s_addc_u32 s1, s3, s1
	v_readlane_b32 s2, v254, 42
	v_cndmask_b32_e32 v34, v34, v35, vcc
	s_add_u32 s0, s0, s2
	v_rsq_f32_e32 v34, v34
	s_addc_u32 s1, s1, 0
	v_lshlrev_b64 v[36:37], 11, v[0:1]
	v_lshl_add_u64 v[36:37], s[0:1], 0, v[36:37]
	v_readlane_b32 s0, v254, 44
	v_readlane_b32 s1, v254, 45
	v_mul_f32_e32 v35, 0x45800000, v34
	v_cndmask_b32_e32 v34, v34, v35, vcc
	v_lshl_add_u64 v[36:37], s[0:1], 1, v[36:37]
	v_readlane_b32 s0, v254, 24
	v_lshlrev_b32_e32 v35, 2, v130
	v_readlane_b32 s1, v254, 25
	v_pk_mul_f32 v[18:19], v[18:19], v[34:35] op_sel_hi:[1,0]
	v_lshlrev_b32_e32 v0, 1, v129
	v_lshl_add_u64 v[36:37], v[36:37], 0, v[0:1]
	v_pk_mul_f32 v[22:23], v[22:23], v[34:35] op_sel_hi:[1,0]
	v_pk_mul_f32 v[2:3], v[2:3], v[34:35] op_sel_hi:[1,0]
	global_load_dwordx4 v[48:51], v35, s[0:1]
	global_load_dwordx4 v[52:55], v35, s[0:1] offset:32
	global_load_dwordx4 v[56:59], v35, s[0:1] offset:64
	global_load_dwordx4 v[60:63], v35, s[0:1] offset:96
	global_load_dwordx4 v[64:67], v35, s[0:1] offset:128
	global_load_dwordx4 v[68:71], v35, s[0:1] offset:160
	global_load_dwordx4 v[72:75], v35, s[0:1] offset:192
	global_load_dwordx4 v[76:79], v35, s[0:1] offset:224
	s_waitcnt vmcnt(0)
	s_nop 1
	v_mov_b64_e32 v[38:39], v[48:49]
	v_mov_b64_e32 v[40:41], v[50:51]
	v_pk_mul_f32 v[6:7], v[6:7], v[34:35] op_sel_hi:[1,0]
	s_movk_i32 s57, 0x88
	s_movk_i32 s56, 0x110
	v_readlane_b32 s3, v254, 40
	v_pk_mul_f32 v[18:19], v[38:39], v[18:19]
	s_nop 0
	v_cvt_pk_bf16_f32 v0, v18, v19
	v_pk_mul_f32 v[18:19], v[20:21], v[34:35] op_sel_hi:[1,0]
	s_nop 0
	v_pk_mul_f32 v[18:19], v[40:41], v[18:19]
	s_nop 0
	v_cvt_pk_bf16_f32 v38, v18, v19
	s_nop 1
	v_mov_b64_e32 v[18:19], v[52:53]
	v_mov_b64_e32 v[20:21], v[54:55]
	v_pk_mul_f32 v[18:19], v[18:19], v[22:23]
	s_nop 0
	v_cvt_pk_bf16_f32 v39, v18, v19
	v_pk_mul_f32 v[18:19], v[24:25], v[34:35] op_sel_hi:[1,0]
	v_pk_mul_f32 v[22:23], v[26:27], v[34:35] op_sel_hi:[1,0]
	v_pk_mul_f32 v[18:19], v[20:21], v[18:19]
	s_nop 0
	v_cvt_pk_bf16_f32 v24, v18, v19
	s_nop 1
	v_mov_b64_e32 v[18:19], v[56:57]
	v_mov_b64_e32 v[20:21], v[58:59]
	v_pk_mul_f32 v[18:19], v[18:19], v[22:23]
	s_nop 0
	v_cvt_pk_bf16_f32 v25, v18, v19
	v_pk_mul_f32 v[18:19], v[28:29], v[34:35] op_sel_hi:[1,0]
	v_pk_mul_f32 v[22:23], v[30:31], v[34:35] op_sel_hi:[1,0]
	v_pk_mul_f32 v[18:19], v[20:21], v[18:19]
	s_nop 0
	v_cvt_pk_bf16_f32 v26, v18, v19
	s_nop 1
	v_mov_b64_e32 v[18:19], v[60:61]
	v_mov_b64_e32 v[20:21], v[62:63]
	v_pk_mul_f32 v[18:19], v[18:19], v[22:23]
	s_nop 0
	v_cvt_pk_bf16_f32 v22, v18, v19
	v_pk_mul_f32 v[18:19], v[32:33], v[34:35] op_sel_hi:[1,0]
	v_cndmask_b32_e64 v29, v25, v22, s[38:39]
	v_pk_mul_f32 v[18:19], v[20:21], v[18:19]
	s_nop 0
	v_cvt_pk_bf16_f32 v23, v18, v19
	v_cndmask_b32_e64 v18, v38, v24, s[38:39]
	v_cndmask_b32_e64 v19, v0, v39, s[38:39]
	ds_bpermute_b32 v27, v128, v19
	ds_bpermute_b32 v18, v128, v18
	v_cndmask_b32_e64 v28, v26, v23, s[38:39]
	s_waitcnt lgkmcnt(1)
	v_cndmask_b32_e64 v20, v39, v27, s[38:39]
	s_waitcnt lgkmcnt(0)
	v_cndmask_b32_e64 v21, v24, v18, s[38:39]
	v_cndmask_b32_e64 v19, v18, v38, s[38:39]
	v_cndmask_b32_e64 v18, v27, v0, s[38:39]
	flat_store_dwordx4 v[36:37], v[18:21] offset:1024
	ds_bpermute_b32 v0, v128, v29
	ds_bpermute_b32 v18, v128, v28
	s_waitcnt lgkmcnt(0)
	v_cndmask_b32_e64 v20, v22, v0, s[38:39]
	v_cndmask_b32_e64 v21, v23, v18, s[38:39]
	v_cndmask_b32_e64 v19, v18, v26, s[38:39]
	v_cndmask_b32_e64 v18, v0, v25, s[38:39]
	flat_store_dwordx4 v[36:37], v[18:21] offset:1056
	s_nop 1
	v_mov_b64_e32 v[18:19], v[64:65]
	v_mov_b64_e32 v[20:21], v[66:67]
	v_pk_mul_f32 v[2:3], v[18:19], v[2:3]
	s_nop 0
	v_cvt_pk_bf16_f32 v0, v2, v3
	v_pk_mul_f32 v[2:3], v[4:5], v[34:35] op_sel_hi:[1,0]
	s_nop 0
	v_pk_mul_f32 v[2:3], v[20:21], v[2:3]
	s_nop 0
	v_cvt_pk_bf16_f32 v18, v2, v3
	s_nop 1
	v_mov_b64_e32 v[2:3], v[68:69]
	v_mov_b64_e32 v[4:5], v[70:71]
	v_pk_mul_f32 v[2:3], v[2:3], v[6:7]
	s_nop 0
	v_cvt_pk_bf16_f32 v19, v2, v3
	v_pk_mul_f32 v[2:3], v[8:9], v[34:35] op_sel_hi:[1,0]
	v_pk_mul_f32 v[6:7], v[10:11], v[34:35] op_sel_hi:[1,0]
	v_pk_mul_f32 v[2:3], v[4:5], v[2:3]
	s_nop 0
	v_cvt_pk_bf16_f32 v8, v2, v3
	s_nop 1
	v_mov_b64_e32 v[2:3], v[72:73]
	v_mov_b64_e32 v[4:5], v[74:75]
	v_pk_mul_f32 v[2:3], v[2:3], v[6:7]
	s_nop 0
	v_cvt_pk_bf16_f32 v9, v2, v3
	v_pk_mul_f32 v[2:3], v[12:13], v[34:35] op_sel_hi:[1,0]
	v_pk_mul_f32 v[6:7], v[14:15], v[34:35] op_sel_hi:[1,0]
	v_pk_mul_f32 v[2:3], v[4:5], v[2:3]
	s_nop 0
	v_cvt_pk_bf16_f32 v10, v2, v3
	s_nop 1
	v_mov_b64_e32 v[2:3], v[76:77]
	v_mov_b64_e32 v[4:5], v[78:79]
	s_mov_b64 s[0:1], 0
	v_pk_mul_f32 v[2:3], v[2:3], v[6:7]
	s_nop 0
	v_cvt_pk_bf16_f32 v6, v2, v3
	v_pk_mul_f32 v[2:3], v[16:17], v[34:35] op_sel_hi:[1,0]
	v_cndmask_b32_e64 v13, v9, v6, s[38:39]
	v_pk_mul_f32 v[2:3], v[4:5], v[2:3]
	s_nop 0
	v_cvt_pk_bf16_f32 v7, v2, v3
	v_cndmask_b32_e64 v2, v18, v8, s[38:39]
	v_cndmask_b32_e64 v3, v0, v19, s[38:39]
	ds_bpermute_b32 v3, v128, v3
	ds_bpermute_b32 v11, v128, v2
	v_cndmask_b32_e64 v12, v10, v7, s[38:39]
	s_waitcnt lgkmcnt(0)
	v_cndmask_b32_e64 v4, v19, v3, s[38:39]
	v_cndmask_b32_e64 v2, v3, v0, s[38:39]
	v_cndmask_b32_e64 v5, v8, v11, s[38:39]
	v_cndmask_b32_e64 v3, v11, v18, s[38:39]
	flat_store_dwordx4 v[36:37], v[2:5] offset:1088
	ds_bpermute_b32 v0, v128, v13
	ds_bpermute_b32 v3, v128, v12
	s_waitcnt lgkmcnt(0)
	v_cndmask_b32_e64 v4, v6, v0, s[38:39]
	v_cndmask_b32_e64 v2, v0, v9, s[38:39]
	v_cndmask_b32_e64 v5, v7, v3, s[38:39]
	v_cndmask_b32_e64 v3, v3, v10, s[38:39]
	flat_store_dwordx4 v[36:37], v[2:5] offset:1120

; template <int MODE>
; DI void attn_unit(LAS unsigned char* lds, const bf16_t* Qg, int ldq, const bf16_t* Kg, int ldk, const bf16_t* VTg, int ldvt, bf16_t* Og, int ldo,
;                   int q0, int NT, const float* gout, const float* relb, float lam, float osc, const float* qgain) {
;     ...
;         if (mm == 0) {
;             float ss = 0.f;
; #pragma unroll
;             for (int d = 0; d < NDB; ++d)
; #pragma unroll
;                 for (int i4 = 0; i4 < 4; ++i4) { const f32x4 x4 = X[(rg * 16 + d * 4 + i4) * 64 + lane];
; #pragma unroll
;                     for (int e = 0; e < 4; ++e) { const float v = o[d][4 * i4 + e] * inv - lam * x4[e]; o[d][4 * i4 + e] = v; ss += v * v; } }
.LBB0_207:
	s_cmpk_gt_u32 s23, 0xff
	s_waitcnt lgkmcnt(0)
	s_barrier
	s_cbranch_scc1 .LBB0_209
	s_lshl_b64 s[0:1], s[16:17], 22
	v_readlane_b32 s2, v254, 12
	v_readlane_b32 s3, v254, 13
	s_add_u32 s0, s2, s0
	s_addc_u32 s1, s3, s1
	s_lshl_b32 s2, s5, 1
	s_add_u32 s0, s0, s2
	s_addc_u32 s1, s1, 0
	s_lshl_b32 s2, s22, 14
	s_add_i32 s2, s2, 0
	v_lshl_add_u32 v70, v183, 4, s2
	ds_read_b128 v[86:89], v70
	ds_read_b128 v[90:93], v70 offset:1024
	ds_read_b128 v[94:97], v70 offset:2048
	ds_read_b128 v[98:101], v70 offset:3072
	ds_read_b128 v[102:105], v70 offset:4096
	ds_read_b128 v[106:109], v70 offset:5120
	ds_read_b128 v[110:113], v70 offset:6144
	ds_read_b128 v[114:117], v70 offset:7168
	ds_read_b128 v[118:121], v70 offset:8192
	ds_read_b128 v[122:125], v70 offset:9216
	ds_read_b128 v[126:129], v70 offset:14336
	ds_read_b128 v[66:69], v70 offset:15360
	s_waitcnt vmcnt(0)
	ds_read_b128 v[130:133], v70 offset:10240
	ds_read_b128 v[134:137], v70 offset:11264
	ds_read_b128 v[138:141], v70 offset:12288
	ds_read_b128 v[142:145], v70 offset:13312
	s_waitcnt lgkmcnt(11)
	v_pk_mul_f32 v[102:103], v[148:149], v[102:103]
	v_pk_mul_f32 v[86:87], v[148:149], v[86:87]
	v_pk_fma_f32 v[102:103], v[34:35], v[0:1], v[102:103] op_sel_hi:[1,0,1] neg_lo:[0,0,1] neg_hi:[0,0,1]
	s_waitcnt lgkmcnt(2)
	v_pk_mul_f32 v[34:35], v[148:149], v[136:137]
	v_pk_mul_f32 v[66:67], v[148:149], v[66:67]
	v_pk_fma_f32 v[32:33], v[32:33], v[0:1], v[34:35] op_sel_hi:[1,0,1] neg_lo:[0,0,1] neg_hi:[0,0,1]
	v_pk_mul_f32 v[34:35], v[148:149], v[134:135]
	v_pk_mul_f32 v[88:89], v[148:149], v[88:89]
	v_pk_fma_f32 v[30:31], v[30:31], v[0:1], v[34:35] op_sel_hi:[1,0,1] neg_lo:[0,0,1] neg_hi:[0,0,1]
	v_pk_mul_f32 v[34:35], v[148:149], v[132:133]
	v_pk_fma_f32 v[50:51], v[50:51], v[0:1], v[86:87] op_sel_hi:[1,0,1] neg_lo:[0,0,1] neg_hi:[0,0,1]
	v_pk_fma_f32 v[28:29], v[28:29], v[0:1], v[34:35] op_sel_hi:[1,0,1] neg_lo:[0,0,1] neg_hi:[0,0,1]
	v_pk_mul_f32 v[34:35], v[148:149], v[130:131]
	v_pk_fma_f32 v[78:79], v[14:15], v[0:1], v[66:67] op_sel_hi:[1,0,1] neg_lo:[0,0,1] neg_hi:[0,0,1]
	v_pk_fma_f32 v[26:27], v[26:27], v[0:1], v[34:35] op_sel_hi:[1,0,1] neg_lo:[0,0,1] neg_hi:[0,0,1]
	v_pk_mul_f32 v[34:35], v[148:149], v[124:125]
	v_pk_mul_f32 v[14:15], v[148:149], v[68:69]
	v_pk_fma_f32 v[24:25], v[24:25], v[0:1], v[34:35] op_sel_hi:[1,0,1] neg_lo:[0,0,1] neg_hi:[0,0,1]
	v_pk_mul_f32 v[34:35], v[148:149], v[122:123]
	v_pk_mul_f32 v[100:101], v[148:149], v[100:101]
	v_pk_fma_f32 v[22:23], v[22:23], v[0:1], v[34:35] op_sel_hi:[1,0,1] neg_lo:[0,0,1] neg_hi:[0,0,1]
	v_pk_mul_f32 v[34:35], v[148:149], v[120:121]
	v_pk_mul_f32 v[98:99], v[148:149], v[98:99]
	v_pk_mul_f32 v[96:97], v[148:149], v[96:97]
	v_pk_mul_f32 v[94:95], v[148:149], v[94:95]
	v_pk_mul_f32 v[92:93], v[148:149], v[92:93]
	v_pk_mul_f32 v[90:91], v[148:149], v[90:91]
	v_pk_fma_f32 v[52:53], v[52:53], v[0:1], v[88:89] op_sel_hi:[1,0,1] neg_lo:[0,0,1] neg_hi:[0,0,1]
	v_pk_mul_f32 v[86:87], v[50:51], v[50:51]
	v_pk_mul_f32 v[116:117], v[148:149], v[116:117]
	v_pk_mul_f32 v[114:115], v[148:149], v[114:115]
	v_pk_mul_f32 v[112:113], v[148:149], v[112:113]
	v_pk_mul_f32 v[110:111], v[148:149], v[110:111]
	v_pk_mul_f32 v[108:109], v[148:149], v[108:109]
	v_pk_mul_f32 v[106:107], v[148:149], v[106:107]
	v_pk_mul_f32 v[104:105], v[148:149], v[104:105]
	v_pk_fma_f32 v[20:21], v[20:21], v[0:1], v[34:35] op_sel_hi:[1,0,1] neg_lo:[0,0,1] neg_hi:[0,0,1]
	v_pk_mul_f32 v[34:35], v[148:149], v[118:119]
	v_pk_mul_f32 v[118:119], v[148:149], v[128:129]
	v_pk_mul_f32 v[126:127], v[148:149], v[126:127]
	s_waitcnt lgkmcnt(0)
	v_pk_mul_f32 v[128:129], v[148:149], v[144:145]
	v_pk_mul_f32 v[142:143], v[148:149], v[142:143]
	v_pk_mul_f32 v[140:141], v[148:149], v[140:141]
	v_pk_mul_f32 v[138:139], v[148:149], v[138:139]
	v_pk_fma_f32 v[80:81], v[16:17], v[0:1], v[14:15] op_sel_hi:[1,0,1] neg_lo:[0,0,1] neg_hi:[0,0,1]
	v_pk_fma_f32 v[64:65], v[64:65], v[0:1], v[100:101] op_sel_hi:[1,0,1] neg_lo:[0,0,1] neg_hi:[0,0,1]
	v_pk_fma_f32 v[62:63], v[62:63], v[0:1], v[98:99] op_sel_hi:[1,0,1] neg_lo:[0,0,1] neg_hi:[0,0,1]
	v_pk_fma_f32 v[60:61], v[60:61], v[0:1], v[96:97] op_sel_hi:[1,0,1] neg_lo:[0,0,1] neg_hi:[0,0,1]
	v_pk_fma_f32 v[58:59], v[58:59], v[0:1], v[94:95] op_sel_hi:[1,0,1] neg_lo:[0,0,1] neg_hi:[0,0,1]
	v_pk_fma_f32 v[56:57], v[56:57], v[0:1], v[92:93] op_sel_hi:[1,0,1] neg_lo:[0,0,1] neg_hi:[0,0,1]
	v_pk_fma_f32 v[54:55], v[54:55], v[0:1], v[90:91] op_sel_hi:[1,0,1] neg_lo:[0,0,1] neg_hi:[0,0,1]
	v_pk_mul_f32 v[88:89], v[52:53], v[52:53]
	v_pk_fma_f32 v[48:49], v[48:49], v[0:1], v[116:117] op_sel_hi:[1,0,1] neg_lo:[0,0,1] neg_hi:[0,0,1]
	v_pk_fma_f32 v[46:47], v[46:47], v[0:1], v[114:115] op_sel_hi:[1,0,1] neg_lo:[0,0,1] neg_hi:[0,0,1]
	v_pk_fma_f32 v[44:45], v[44:45], v[0:1], v[112:113] op_sel_hi:[1,0,1] neg_lo:[0,0,1] neg_hi:[0,0,1]
	v_pk_fma_f32 v[42:43], v[42:43], v[0:1], v[110:111] op_sel_hi:[1,0,1] neg_lo:[0,0,1] neg_hi:[0,0,1]
	v_pk_fma_f32 v[40:41], v[40:41], v[0:1], v[108:109] op_sel_hi:[1,0,1] neg_lo:[0,0,1] neg_hi:[0,0,1]
	v_pk_fma_f32 v[38:39], v[38:39], v[0:1], v[106:107] op_sel_hi:[1,0,1] neg_lo:[0,0,1] neg_hi:[0,0,1]
	v_pk_fma_f32 v[36:37], v[36:37], v[0:1], v[104:105] op_sel_hi:[1,0,1] neg_lo:[0,0,1] neg_hi:[0,0,1]
	v_pk_fma_f32 v[34:35], v[18:19], v[0:1], v[34:35] op_sel_hi:[1,0,1] neg_lo:[0,0,1] neg_hi:[0,0,1]
	v_pk_fma_f32 v[12:13], v[12:13], v[0:1], v[118:119] op_sel_hi:[1,0,1] neg_lo:[0,0,1] neg_hi:[0,0,1]
	v_pk_fma_f32 v[10:11], v[10:11], v[0:1], v[126:127] op_sel_hi:[1,0,1] neg_lo:[0,0,1] neg_hi:[0,0,1]
	v_pk_fma_f32 v[8:9], v[8:9], v[0:1], v[128:129] op_sel_hi:[1,0,1] neg_lo:[0,0,1] neg_hi:[0,0,1]
; DI unsigned cvtpk(float lo, float hi) { f32x2_t v = {lo, hi}; bf16x2_t b = __builtin_convertvector(v, bf16x2_t); return __builtin_bit_cast(unsigned, b); }
; DI float shx(float v, int mask, int lane) { return __builtin_bit_cast(float, __builtin_amdgcn_ds_bpermute((lane ^ mask) << 2, __builtin_bit_cast(int, v))); }
; template <int MODE>
; DI void attn_unit(LAS unsigned char* lds, const bf16_t* Qg, int ldq, const bf16_t* Kg, int ldk, const bf16_t* VTg, int ldvt, bf16_t* Og, int ldo,
;                   int q0, int NT, const float* gout, const float* relb, float lam, float osc, const float* qgain) {
;     ...
;             ss += shx(ss, 32, lane);
;             const float rs = rsqrtf(ss * (1.f / 128.f) + EPS) * osc;
;             bf16_t* opb = Og + (size_t)qrow * ldo;
; #pragma unroll
;             for (int d = 0; d < NDB; ++d) { u32x2 wq[4];
; #pragma unroll
;                 for (int g = 0; g < 4; ++g) { const f32x4 gv = *(const f32x4*)(gout + 32 * d + 8 * g + 4 * hi);
;                     u32x2 w; w.x = cvtpk(o[d][4 * g] * rs * gv[0], o[d][4 * g + 1] * rs * gv[1]); w.y = cvtpk(o[d][4 * g + 2] * rs * gv[2], o[d][4 * g + 3] * rs * gv[3]);
;                     wq[g] = w; }
;                 AT_STORE16(opb, d); }
	v_pk_fma_f32 v[6:7], v[6:7], v[0:1], v[142:143] op_sel_hi:[1,0,1] neg_lo:[0,0,1] neg_hi:[0,0,1]
	v_pk_fma_f32 v[4:5], v[4:5], v[0:1], v[140:141] op_sel_hi:[1,0,1] neg_lo:[0,0,1] neg_hi:[0,0,1]
	v_pk_fma_f32 v[2:3], v[2:3], v[0:1], v[138:139] op_sel_hi:[1,0,1] neg_lo:[0,0,1] neg_hi:[0,0,1]
	v_add_f32_e32 v0, v86, v87
	v_readlane_b32 s2, v254, 30
	v_add_f32_e32 v0, v88, v0
	v_readlane_b32 s3, v254, 31
	v_pk_mul_f32 v[90:91], v[54:55], v[54:55]
	v_add_f32_e32 v0, v89, v0
	s_nop 2
	global_load_dwordx4 v[74:77], v150, s[2:3]
	global_load_dwordx4 v[70:73], v150, s[2:3] offset:32
	global_load_dwordx4 v[66:69], v150, s[2:3] offset:64
	global_load_dwordx4 v[14:17], v150, s[2:3] offset:96
	global_load_dwordx4 v[196:199], v150, s[2:3] offset:128
	global_load_dwordx4 v[200:203], v150, s[2:3] offset:160
	global_load_dwordx4 v[204:207], v150, s[2:3] offset:192
	global_load_dwordx4 v[208:211], v150, s[2:3] offset:224
	global_load_dwordx4 v[212:215], v150, s[2:3] offset:256
	global_load_dwordx4 v[216:219], v150, s[2:3] offset:288
	global_load_dwordx4 v[220:223], v150, s[2:3] offset:320
	global_load_dwordx4 v[224:227], v150, s[2:3] offset:352
	global_load_dwordx4 v[172:175], v150, s[2:3] offset:384
	global_load_dwordx4 v[176:179], v150, s[2:3] offset:416
	global_load_dwordx4 v[236:239], v150, s[2:3] offset:448
	global_load_dwordx4 v[240:243], v150, s[2:3] offset:480
	v_add_f32_e32 v0, v90, v0
	v_pk_mul_f32 v[92:93], v[56:57], v[56:57]
	v_add_f32_e32 v0, v91, v0
	v_add_f32_e32 v0, v92, v0
	v_pk_mul_f32 v[94:95], v[58:59], v[58:59]
	v_add_f32_e32 v0, v93, v0
	v_add_f32_e32 v0, v94, v0
	v_pk_mul_f32 v[96:97], v[60:61], v[60:61]
	v_add_f32_e32 v0, v95, v0
	v_add_f32_e32 v0, v96, v0
	v_pk_mul_f32 v[98:99], v[62:63], v[62:63]
	v_add_f32_e32 v0, v97, v0
	v_add_f32_e32 v0, v98, v0
	v_pk_mul_f32 v[100:101], v[64:65], v[64:65]
	v_add_f32_e32 v0, v99, v0
	v_add_f32_e32 v0, v100, v0
	v_pk_mul_f32 v[146:147], v[102:103], v[102:103]
	v_add_f32_e32 v0, v101, v0
	v_add_f32_e32 v0, v146, v0
	v_pk_mul_f32 v[104:105], v[36:37], v[36:37]
	v_add_f32_e32 v0, v147, v0
	v_add_f32_e32 v0, v104, v0
	v_pk_mul_f32 v[106:107], v[38:39], v[38:39]
	v_add_f32_e32 v0, v105, v0
	v_add_f32_e32 v0, v106, v0
	v_pk_mul_f32 v[108:109], v[40:41], v[40:41]
	v_add_f32_e32 v0, v107, v0
	v_add_f32_e32 v0, v108, v0
	v_pk_mul_f32 v[110:111], v[42:43], v[42:43]
	v_add_f32_e32 v0, v109, v0
	v_add_f32_e32 v0, v110, v0
	v_pk_mul_f32 v[112:113], v[44:45], v[44:45]
	v_add_f32_e32 v0, v111, v0
	v_add_f32_e32 v0, v112, v0
	v_pk_mul_f32 v[114:115], v[46:47], v[46:47]
	v_add_f32_e32 v0, v113, v0
	v_add_f32_e32 v0, v114, v0
	v_pk_mul_f32 v[116:117], v[48:49], v[48:49]
	v_add_f32_e32 v0, v115, v0
	v_add_f32_e32 v0, v116, v0
	v_pk_mul_f32 v[18:19], v[34:35], v[34:35]
	v_add_f32_e32 v0, v117, v0
	v_add_f32_e32 v0, v18, v0
	v_pk_mul_f32 v[120:121], v[20:21], v[20:21]
	v_add_f32_e32 v0, v19, v0
	v_add_f32_e32 v0, v120, v0
	v_pk_mul_f32 v[122:123], v[22:23], v[22:23]
	v_add_f32_e32 v0, v121, v0
	v_add_f32_e32 v0, v122, v0
	v_pk_mul_f32 v[124:125], v[24:25], v[24:25]
	v_add_f32_e32 v0, v123, v0
	v_add_f32_e32 v0, v124, v0
	v_pk_mul_f32 v[130:131], v[26:27], v[26:27]
	v_add_f32_e32 v0, v125, v0
	v_add_f32_e32 v0, v130, v0
	v_pk_mul_f32 v[132:133], v[28:29], v[28:29]
	v_add_f32_e32 v0, v131, v0
	v_add_f32_e32 v0, v132, v0
	v_pk_mul_f32 v[134:135], v[30:31], v[30:31]
	v_add_f32_e32 v0, v133, v0
	v_add_f32_e32 v0, v134, v0
	v_pk_mul_f32 v[136:137], v[32:33], v[32:33]
	v_add_f32_e32 v0, v135, v0
	v_add_f32_e32 v0, v136, v0
	v_pk_mul_f32 v[138:139], v[2:3], v[2:3]
	v_add_f32_e32 v0, v137, v0
	v_add_f32_e32 v0, v138, v0
	v_pk_mul_f32 v[140:141], v[4:5], v[4:5]
	v_add_f32_e32 v0, v139, v0
	v_add_f32_e32 v0, v140, v0
	v_pk_mul_f32 v[142:143], v[6:7], v[6:7]
	v_add_f32_e32 v0, v141, v0
	v_add_f32_e32 v0, v142, v0
	v_pk_mul_f32 v[128:129], v[8:9], v[8:9]
	v_add_f32_e32 v0, v143, v0
	v_add_f32_e32 v0, v128, v0
	v_pk_mul_f32 v[126:127], v[10:11], v[10:11]
	v_add_f32_e32 v0, v129, v0
	v_add_f32_e32 v0, v126, v0
	v_pk_mul_f32 v[118:119], v[12:13], v[12:13]
	v_add_f32_e32 v0, v127, v0
	v_add_f32_e32 v0, v118, v0
	v_pk_mul_f32 v[82:83], v[78:79], v[78:79]
	v_add_f32_e32 v0, v119, v0
	v_add_f32_e32 v0, v82, v0
	v_pk_mul_f32 v[84:85], v[80:81], v[80:81]
	v_add_f32_e32 v0, v83, v0
	v_add_f32_e32 v0, v84, v0
	v_add_f32_e32 v18, v85, v0
	ds_bpermute_b32 v19, v151, v18
	v_lshlrev_b32_e32 v0, 11, v182
	s_waitcnt lgkmcnt(0)
	v_add_f32_e32 v18, v18, v19
	v_fmamk_f32 v18, v18, 0x3c000000, v228
	v_mul_f32_e32 v19, 0x4b800000, v18
	v_cmp_gt_f32_e32 vcc, s52, v18
	s_nop 1
	v_cndmask_b32_e32 v18, v18, v19, vcc
	v_rsq_f32_e32 v82, v18
	v_lshl_add_u64 v[18:19], s[0:1], 0, v[0:1]
	v_lshlrev_b32_e32 v0, 1, v184
	v_lshl_add_u64 v[18:19], v[18:19], 0, v[0:1]
	v_mul_f32_e32 v0, 0x45800000, v82
	v_cndmask_b32_e32 v0, v82, v0, vcc
	v_mul_f32_e32 v0, v181, v0
	v_pk_mul_f32 v[50:51], v[50:51], v[0:1] op_sel_hi:[1,0]
	v_cmp_gt_u32_e32 vcc, 32, v183
	s_waitcnt vmcnt(3)
	v_pk_mul_f32 v[50:51], v[74:75], v[50:51]
	v_pk_mul_f32 v[34:35], v[34:35], v[0:1] op_sel_hi:[1,0]
	v_cvt_pk_bf16_f32 v74, v50, v51
	v_pk_mul_f32 v[50:51], v[52:53], v[0:1] op_sel_hi:[1,0]
	v_pk_mul_f32 v[2:3], v[2:3], v[0:1] op_sel_hi:[1,0]
	v_pk_mul_f32 v[50:51], v[76:77], v[50:51]
	v_pk_mul_f32 v[6:7], v[6:7], v[0:1] op_sel_hi:[1,0]
	v_cvt_pk_bf16_f32 v52, v50, v51
	v_pk_mul_f32 v[50:51], v[54:55], v[0:1] op_sel_hi:[1,0]
	v_pk_mul_f32 v[10:11], v[10:11], v[0:1] op_sel_hi:[1,0]
	s_waitcnt vmcnt(2)
; DI unsigned cvtpk(float lo, float hi) { f32x2_t v = {lo, hi}; bf16x2_t b = __builtin_convertvector(v, bf16x2_t); return __builtin_bit_cast(unsigned, b); }
; template <int MODE>
; DI void attn_unit(LAS unsigned char* lds, const bf16_t* Qg, int ldq, const bf16_t* Kg, int ldk, const bf16_t* VTg, int ldvt, bf16_t* Og, int ldo,
;                   int q0, int NT, const float* gout, const float* relb, float lam, float osc, const float* qgain) {
;     ...
;             for (int d = 0; d < NDB; ++d) { u32x2 wq[4];
; #pragma unroll
;                 for (int g = 0; g < 4; ++g) { const f32x4 gv = *(const f32x4*)(gout + 32 * d + 8 * g + 4 * hi);
;                     u32x2 w; w.x = cvtpk(o[d][4 * g] * rs * gv[0], o[d][4 * g + 1] * rs * gv[1]); w.y = cvtpk(o[d][4 * g + 2] * rs * gv[2], o[d][4 * g + 3] * rs * gv[3]);
;                     wq[g] = w; }
;                 AT_STORE16(opb, d); }
	v_pk_mul_f32 v[50:51], v[70:71], v[50:51]
	v_pk_mul_f32 v[4:5], v[4:5], v[0:1] op_sel_hi:[1,0]
	v_cvt_pk_bf16_f32 v53, v50, v51
	v_pk_mul_f32 v[50:51], v[56:57], v[0:1] op_sel_hi:[1,0]
	v_pk_mul_f32 v[8:9], v[8:9], v[0:1] op_sel_hi:[1,0]
	v_pk_mul_f32 v[50:51], v[72:73], v[50:51]
	v_pk_mul_f32 v[12:13], v[12:13], v[0:1] op_sel_hi:[1,0]
	v_cvt_pk_bf16_f32 v54, v50, v51
	v_pk_mul_f32 v[50:51], v[58:59], v[0:1] op_sel_hi:[1,0]
	s_waitcnt vmcnt(1)
	v_pk_mul_f32 v[50:51], v[66:67], v[50:51]
	s_nop 0
	v_cvt_pk_bf16_f32 v55, v50, v51
	v_pk_mul_f32 v[50:51], v[60:61], v[0:1] op_sel_hi:[1,0]
	s_nop 0
	v_pk_mul_f32 v[50:51], v[68:69], v[50:51]
	s_nop 0
	v_cvt_pk_bf16_f32 v56, v50, v51
	v_pk_mul_f32 v[50:51], v[62:63], v[0:1] op_sel_hi:[1,0]
	v_pk_mul_f32 v[62:63], v[102:103], v[0:1] op_sel_hi:[1,0]
	s_waitcnt vmcnt(0)
	v_pk_mul_f32 v[14:15], v[14:15], v[50:51]
	s_nop 0
	v_cvt_pk_bf16_f32 v50, v14, v15
	v_pk_mul_f32 v[14:15], v[64:65], v[0:1] op_sel_hi:[1,0]
	s_nop 0
	v_pk_mul_f32 v[14:15], v[16:17], v[14:15]
	v_cndmask_b32_e32 v16, v52, v54, vcc
	v_cndmask_b32_e32 v17, v74, v53, vcc
	ds_bpermute_b32 v51, v151, v16
	ds_bpermute_b32 v57, v151, v17
	v_cvt_pk_bf16_f32 v58, v14, v15
	v_cndmask_b32_e32 v14, v56, v58, vcc
	v_cndmask_b32_e32 v15, v55, v50, vcc
	s_waitcnt lgkmcnt(1)
	v_cndmask_b32_e32 v17, v54, v51, vcc
	s_waitcnt lgkmcnt(0)
	v_cndmask_b32_e32 v16, v53, v57, vcc
	ds_bpermute_b32 v53, v151, v14
	ds_bpermute_b32 v54, v151, v15
	v_cndmask_b32_e32 v15, v51, v52, vcc
	v_cndmask_b32_e32 v14, v57, v74, vcc
	flat_store_dwordx4 v[18:19], v[14:17]
	s_waitcnt lgkmcnt(0)
	s_nop 0
	v_cndmask_b32_e32 v17, v58, v53, vcc
	v_cndmask_b32_e32 v16, v50, v54, vcc
	v_cndmask_b32_e32 v15, v53, v56, vcc
	v_cndmask_b32_e32 v14, v54, v55, vcc
	flat_store_dwordx4 v[18:19], v[14:17] offset:32
	v_mov_b64_e32 v[50:51], v[200:201]
	v_mov_b64_e32 v[52:53], v[202:203]
	v_mov_b64_e32 v[54:55], v[204:205]
	v_mov_b64_e32 v[56:57], v[206:207]
	v_mov_b64_e32 v[58:59], v[208:209]
	v_mov_b64_e32 v[60:61], v[210:211]
	v_mov_b64_e32 v[14:15], v[196:197]
	v_mov_b64_e32 v[16:17], v[198:199]
	v_pk_mul_f32 v[14:15], v[14:15], v[62:63]
	s_nop 0
	v_cvt_pk_bf16_f32 v62, v14, v15
	v_pk_mul_f32 v[14:15], v[36:37], v[0:1] op_sel_hi:[1,0]
	s_nop 0
	v_pk_mul_f32 v[14:15], v[16:17], v[14:15]
	s_nop 0
	v_cvt_pk_bf16_f32 v36, v14, v15
	v_pk_mul_f32 v[14:15], v[38:39], v[0:1] op_sel_hi:[1,0]
	s_nop 0
	v_pk_mul_f32 v[14:15], v[50:51], v[14:15]
	s_nop 0
	v_cvt_pk_bf16_f32 v16, v14, v15
	v_pk_mul_f32 v[14:15], v[40:41], v[0:1] op_sel_hi:[1,0]
	s_nop 0
	v_pk_mul_f32 v[14:15], v[52:53], v[14:15]
	s_nop 0
	v_cvt_pk_bf16_f32 v17, v14, v15
	v_pk_mul_f32 v[14:15], v[42:43], v[0:1] op_sel_hi:[1,0]
	s_nop 0
	v_pk_mul_f32 v[14:15], v[54:55], v[14:15]
	s_nop 0
	v_cvt_pk_bf16_f32 v37, v14, v15
	v_pk_mul_f32 v[14:15], v[44:45], v[0:1] op_sel_hi:[1,0]
	s_nop 0
	v_pk_mul_f32 v[14:15], v[56:57], v[14:15]
	s_nop 0
	v_cvt_pk_bf16_f32 v38, v14, v15
	v_pk_mul_f32 v[14:15], v[46:47], v[0:1] op_sel_hi:[1,0]
	s_nop 0
	v_pk_mul_f32 v[14:15], v[58:59], v[14:15]
	s_nop 0
	v_cvt_pk_bf16_f32 v39, v14, v15
	v_pk_mul_f32 v[14:15], v[48:49], v[0:1] op_sel_hi:[1,0]
	v_cndmask_b32_e32 v42, v37, v39, vcc
	v_pk_mul_f32 v[14:15], v[60:61], v[14:15]
	ds_bpermute_b32 v42, v151, v42
	v_cvt_pk_bf16_f32 v40, v14, v15
	v_cndmask_b32_e32 v14, v62, v16, vcc
	v_cndmask_b32_e32 v15, v36, v17, vcc
	ds_bpermute_b32 v14, v151, v14
	ds_bpermute_b32 v15, v151, v15
	v_cndmask_b32_e32 v41, v38, v40, vcc
	ds_bpermute_b32 v41, v151, v41
	s_waitcnt lgkmcnt(0)
; DI unsigned cvtpk(float lo, float hi) { f32x2_t v = {lo, hi}; bf16x2_t b = __builtin_convertvector(v, bf16x2_t); return __builtin_bit_cast(unsigned, b); }
; template <int MODE>
; DI void attn_unit(LAS unsigned char* lds, const bf16_t* Qg, int ldq, const bf16_t* Kg, int ldk, const bf16_t* VTg, int ldvt, bf16_t* Og, int ldo,
;                   int q0, int NT, const float* gout, const float* relb, float lam, float osc, const float* qgain) {
;     ...
;             for (int d = 0; d < NDB; ++d) { u32x2 wq[4];
; #pragma unroll
;                 for (int g = 0; g < 4; ++g) { const f32x4 gv = *(const f32x4*)(gout + 32 * d + 8 * g + 4 * hi);
;                     u32x2 w; w.x = cvtpk(o[d][4 * g] * rs * gv[0], o[d][4 * g + 1] * rs * gv[1]); w.y = cvtpk(o[d][4 * g + 2] * rs * gv[2], o[d][4 * g + 3] * rs * gv[3]);
;                     wq[g] = w; }
;                 AT_STORE16(opb, d); }
	v_cndmask_b32_e32 v16, v16, v14, vcc
	v_cndmask_b32_e32 v14, v14, v62, vcc
	v_cndmask_b32_e32 v17, v17, v15, vcc
	v_cndmask_b32_e32 v15, v15, v36, vcc
	flat_store_dwordx4 v[18:19], v[14:17] offset:64
	s_nop 1
	v_cndmask_b32_e32 v16, v39, v42, vcc
	v_cndmask_b32_e32 v14, v42, v37, vcc
	v_cndmask_b32_e32 v17, v40, v41, vcc
	v_cndmask_b32_e32 v15, v41, v38, vcc
	flat_store_dwordx4 v[18:19], v[14:17] offset:96
	v_mov_b64_e32 v[36:37], v[216:217]
	v_mov_b64_e32 v[38:39], v[218:219]
	v_mov_b64_e32 v[40:41], v[220:221]
	v_mov_b64_e32 v[42:43], v[222:223]
	v_mov_b64_e32 v[44:45], v[224:225]
	v_mov_b64_e32 v[46:47], v[226:227]
	v_mov_b64_e32 v[14:15], v[212:213]
	v_mov_b64_e32 v[16:17], v[214:215]
	v_pk_mul_f32 v[14:15], v[14:15], v[34:35]
	s_nop 0
	v_cvt_pk_bf16_f32 v34, v14, v15
	v_pk_mul_f32 v[14:15], v[20:21], v[0:1] op_sel_hi:[1,0]
	s_nop 0
	v_pk_mul_f32 v[14:15], v[16:17], v[14:15]
	s_nop 0
	v_cvt_pk_bf16_f32 v20, v14, v15
	v_pk_mul_f32 v[14:15], v[22:23], v[0:1] op_sel_hi:[1,0]
	s_nop 0
	v_pk_mul_f32 v[14:15], v[36:37], v[14:15]
	s_nop 0
	v_cvt_pk_bf16_f32 v16, v14, v15
	v_pk_mul_f32 v[14:15], v[24:25], v[0:1] op_sel_hi:[1,0]
	s_nop 0
	v_pk_mul_f32 v[14:15], v[38:39], v[14:15]
	s_nop 0
	v_cvt_pk_bf16_f32 v17, v14, v15
	v_pk_mul_f32 v[14:15], v[26:27], v[0:1] op_sel_hi:[1,0]
	s_nop 0
	v_pk_mul_f32 v[14:15], v[40:41], v[14:15]
	s_nop 0
	v_cvt_pk_bf16_f32 v21, v14, v15
	v_pk_mul_f32 v[14:15], v[28:29], v[0:1] op_sel_hi:[1,0]
	s_nop 0
	v_pk_mul_f32 v[14:15], v[42:43], v[14:15]
	s_nop 0
	v_cvt_pk_bf16_f32 v22, v14, v15
	v_pk_mul_f32 v[14:15], v[30:31], v[0:1] op_sel_hi:[1,0]
	s_nop 0
	v_pk_mul_f32 v[14:15], v[44:45], v[14:15]
	s_nop 0
	v_cvt_pk_bf16_f32 v23, v14, v15
	v_pk_mul_f32 v[14:15], v[32:33], v[0:1] op_sel_hi:[1,0]
	v_cndmask_b32_e32 v26, v21, v23, vcc
	v_pk_mul_f32 v[14:15], v[46:47], v[14:15]
	ds_bpermute_b32 v26, v151, v26
	v_cvt_pk_bf16_f32 v24, v14, v15
	v_cndmask_b32_e32 v14, v34, v16, vcc
	v_cndmask_b32_e32 v15, v20, v17, vcc
	ds_bpermute_b32 v14, v151, v14
	ds_bpermute_b32 v15, v151, v15
	v_cndmask_b32_e32 v25, v22, v24, vcc
	ds_bpermute_b32 v25, v151, v25
	v_pk_mul_f32 v[32:33], v[78:79], v[0:1] op_sel_hi:[1,0]
	s_waitcnt lgkmcnt(0)
	v_cndmask_b32_e32 v16, v16, v14, vcc
	v_cndmask_b32_e32 v14, v14, v34, vcc
	v_cndmask_b32_e32 v17, v17, v15, vcc
	v_cndmask_b32_e32 v15, v15, v20, vcc
	flat_store_dwordx4 v[18:19], v[14:17] offset:128
	v_pk_mul_f32 v[34:35], v[80:81], v[0:1] op_sel_hi:[1,0]
	s_nop 0
	v_cndmask_b32_e32 v16, v23, v26, vcc
	v_cndmask_b32_e32 v14, v26, v21, vcc
	v_cndmask_b32_e32 v17, v24, v25, vcc
	v_cndmask_b32_e32 v15, v25, v22, vcc
	flat_store_dwordx4 v[18:19], v[14:17] offset:160
	v_mov_b64_e32 v[20:21], v[176:177]
	v_mov_b64_e32 v[22:23], v[178:179]
	v_mov_b64_e32 v[24:25], v[236:237]
	v_mov_b64_e32 v[26:27], v[238:239]
	v_mov_b64_e32 v[28:29], v[240:241]
	v_mov_b64_e32 v[30:31], v[242:243]
	v_mov_b64_e32 v[14:15], v[172:173]
	v_mov_b64_e32 v[16:17], v[174:175]
	v_pk_mul_f32 v[2:3], v[14:15], v[2:3]
	v_pk_mul_f32 v[6:7], v[20:21], v[6:7]
	v_pk_mul_f32 v[10:11], v[24:25], v[10:11]
	v_cvt_pk_bf16_f32 v0, v2, v3
	v_cvt_pk_bf16_f32 v2, v6, v7
	v_cvt_pk_bf16_f32 v6, v10, v11
	v_cndmask_b32_e32 v10, v0, v2, vcc
	ds_bpermute_b32 v10, v151, v10
	v_pk_mul_f32 v[4:5], v[16:17], v[4:5]
	v_pk_mul_f32 v[8:9], v[22:23], v[8:9]
	v_pk_mul_f32 v[12:13], v[26:27], v[12:13]
	v_pk_mul_f32 v[14:15], v[28:29], v[32:33]
	v_pk_mul_f32 v[16:17], v[30:31], v[34:35]
	v_cvt_pk_bf16_f32 v3, v4, v5
	v_cvt_pk_bf16_f32 v5, v8, v9
	v_cvt_pk_bf16_f32 v7, v12, v13
	v_cvt_pk_bf16_f32 v8, v14, v15
	v_cvt_pk_bf16_f32 v9, v16, v17
	v_cndmask_b32_e32 v4, v3, v5, vcc
	v_cndmask_b32_e32 v11, v7, v9, vcc
	ds_bpermute_b32 v12, v151, v4
	v_cndmask_b32_e32 v4, v6, v8, vcc
	ds_bpermute_b32 v13, v151, v4
	s_waitcnt lgkmcnt(0)
	v_cndmask_b32_e32 v4, v2, v10, vcc
	v_cndmask_b32_e32 v2, v10, v0, vcc
	ds_bpermute_b32 v0, v151, v11
	v_cndmask_b32_e32 v5, v5, v12, vcc
	v_cndmask_b32_e32 v3, v12, v3, vcc
	flat_store_dwordx4 v[18:19], v[2:5] offset:192
	s_nop 1
	v_cndmask_b32_e32 v4, v8, v13, vcc
	v_cndmask_b32_e32 v2, v13, v6, vcc
	s_waitcnt lgkmcnt(0)
	v_cndmask_b32_e32 v5, v9, v0, vcc
	v_cndmask_b32_e32 v3, v0, v7, vcc
	flat_store_dwordx4 v[18:19], v[2:5] offset:224
